# attention loop re-pipelined in 32-key half-tile steps: QK of next half and PV of previous half interleaved with exp/sum/pack VALU, 4-stage LDS-DMA ring, fragment prefetch one step ahead
# speedup vs baseline: 1.0893x; 1.0352x over previous
.LBB0_350:
	s_lshl_b32 s0, s2, 14
	s_add_u32 s76, s94, s0
	s_addc_u32 s77, s95, 0
	s_add_u32 s76, s76, 0x6bc0000
	s_addc_u32 s77, s77, 0
	s_lshr_b32 s0, s2, 7
	s_mul_i32 s0, s0, 0x108000
	s_add_u32 s78, s94, s0
	s_addc_u32 s79, s95, 0
	s_add_u32 s78, s78, 0x7400000
	s_addc_u32 s79, s79, 0
	s_add_u32 s80, s78, 0x420000
	s_addc_u32 s81, s79, 0
	v_and_b32_e32 v136, 31, v138
	v_bfe_u32 v137, v138, 5, 1
	v_lshrrev_b32_e32 v167, 6, v138
	v_lshl_add_u32 v171, v167, 5, v136
	v_readfirstlane_b32 s83, v167
	v_lshlrev_b32_e32 v171, 7, v171
	v_lshl_add_u32 v171, v137, 4, v171
	s_lshl_b32 s83, s83, 11
	global_load_dwordx4 v[96:99], v171, s[76:77]
	global_load_dwordx4 v[100:103], v171, s[76:77] offset:32
	global_load_dwordx4 v[104:107], v171, s[76:77] offset:64
	global_load_dwordx4 v[108:111], v171, s[76:77] offset:96
	v_and_b32_e32 v168, 0x13, v136
	v_and_b32_e32 v169, 4, v136
	v_lshl_or_b32 v168, v169, 1, v168
	v_and_b32_e32 v169, 8, v136
	v_lshrrev_b32_e32 v169, 1, v169
	v_or_b32_e32 v168, v168, v169
	v_bfe_u32 v170, v168, 1, 3
	v_xor_b32_e32 v170, v170, v137
	v_lshlrev_b32_e32 v170, 4, v170
	v_lshlrev_b32_e32 v168, 7, v168
	v_add_u32_e32 v244, v168, v170
	v_xor_b32_e32 v169, 32, v170
	v_add_u32_e32 v245, v168, v169
	v_xor_b32_e32 v169, 64, v170
	v_add_u32_e32 v246, v168, v169
	v_xor_b32_e32 v169, 96, v170
	v_add_u32_e32 v247, v168, v169
	v_bfe_u32 v170, v136, 1, 3
	v_xor_b32_e32 v170, v170, v137
	v_lshlrev_b32_e32 v170, 4, v170
	v_lshlrev_b32_e32 v168, 7, v136
	v_add_u32_e32 v248, v168, v170
	v_xor_b32_e32 v169, 32, v170
	v_add_u32_e32 v249, v168, v169
	v_xor_b32_e32 v169, 64, v170
	v_add_u32_e32 v250, v168, v169
	v_xor_b32_e32 v169, 96, v170
	v_add_u32_e32 v251, v168, v169
	v_bfe_u32 v168, v138, 3, 3
	v_and_b32_e32 v169, 7, v138
	v_lshrrev_b32_e32 v170, 1, v168
	v_xor_b32_e32 v170, v170, v169
	v_lshl_add_u32 v171, v167, 4, v168
	v_lshlrev_b32_e32 v169, 7, v171
	v_lshl_add_u32 v252, v170, 4, v169
	v_xor_b32_e32 v168, 4, v170
	v_lshl_add_u32 v253, v168, 4, v169
	s_movk_i32 s0, 0x4200
	v_mul_lo_u32 v169, v171, s0
	v_lshl_add_u32 v254, v170, 4, v169
	v_lshl_add_u32 v255, v168, 4, v169
	v_add_u32_e32 v255, 134144, v255
	s_barrier
	s_add_i32 m0, s83, 0
	s_nop 0
	global_load_lds_dwordx4 v252, s[78:79]
	global_load_lds_dwordx4 v253, s[78:79] offset:1024
	s_add_i32 m0, s83, 8192
	s_nop 0
	global_load_lds_dwordx4 v254, s[80:81]
	global_load_lds_dwordx4 v255, s[80:81] offset:1024
	s_add_u32 s78, s78, 0x2000
	s_addc_u32 s79, s79, 0
	s_add_u32 s80, s80, 0x80
	s_addc_u32 s81, s81, 0
	s_add_i32 m0, s83, 16384
	s_nop 0
	global_load_lds_dwordx4 v252, s[78:79]
	global_load_lds_dwordx4 v253, s[78:79] offset:1024
	s_add_i32 m0, s83, 24576
	s_nop 0
	global_load_lds_dwordx4 v254, s[80:81]
	global_load_lds_dwordx4 v255, s[80:81] offset:1024
	s_add_u32 s78, s78, 0x2000
	s_addc_u32 s79, s79, 0
	s_add_u32 s80, s80, 0x80
	s_addc_u32 s81, s81, 0
	v_mov_b32_e32 v32, 0
	v_mov_b32_e32 v33, 0
	v_mov_b32_e32 v34, 0
	v_mov_b32_e32 v35, 0
	v_mov_b32_e32 v36, 0
	v_mov_b32_e32 v37, 0
	v_mov_b32_e32 v38, 0
	v_mov_b32_e32 v39, 0
	v_mov_b32_e32 v40, 0
	v_mov_b32_e32 v41, 0
	v_mov_b32_e32 v42, 0
	v_mov_b32_e32 v43, 0
	v_mov_b32_e32 v44, 0
	v_mov_b32_e32 v45, 0
	v_mov_b32_e32 v46, 0
	v_mov_b32_e32 v47, 0
	v_mov_b32_e32 v48, 0
	v_mov_b32_e32 v49, 0
	v_mov_b32_e32 v50, 0
	v_mov_b32_e32 v51, 0
	v_mov_b32_e32 v52, 0
	v_mov_b32_e32 v53, 0
	v_mov_b32_e32 v54, 0
	v_mov_b32_e32 v55, 0
	v_mov_b32_e32 v56, 0
	v_mov_b32_e32 v57, 0
	v_mov_b32_e32 v58, 0
	v_mov_b32_e32 v59, 0
	v_mov_b32_e32 v60, 0
	v_mov_b32_e32 v61, 0
	v_mov_b32_e32 v62, 0
	v_mov_b32_e32 v63, 0
	v_mov_b32_e32 v80, 0
	v_mov_b32_e32 v81, 0
	v_mov_b32_e32 v82, 0
	v_mov_b32_e32 v83, 0
	v_mov_b32_e32 v84, 0
	v_mov_b32_e32 v85, 0
	v_mov_b32_e32 v86, 0
	v_mov_b32_e32 v87, 0
	v_mov_b32_e32 v88, 0
	v_mov_b32_e32 v89, 0
	v_mov_b32_e32 v90, 0
	v_mov_b32_e32 v91, 0
	v_mov_b32_e32 v92, 0
	v_mov_b32_e32 v93, 0
	v_mov_b32_e32 v94, 0
	v_mov_b32_e32 v95, 0
	v_mov_b32_e32 v192, 0
	v_mov_b32_e32 v193, 0
	v_mov_b32_e32 v194, 0
	v_mov_b32_e32 v195, 0
	v_mov_b32_e32 v196, 0
	v_mov_b32_e32 v197, 0
	v_mov_b32_e32 v198, 0
	v_mov_b32_e32 v199, 0
	v_mov_b32_e32 v200, 0
	v_mov_b32_e32 v201, 0
	v_mov_b32_e32 v202, 0
	v_mov_b32_e32 v203, 0
	v_mov_b32_e32 v240, 0
	v_mov_b32_e32 v241, 0
	v_mov_b32_e32 v242, 0
	v_mov_b32_e32 v243, 0
	v_mov_b32_e32 v128, 0
	v_mov_b32_e32 v129, 0
	s_mov_b32 s84, 0
	s_mov_b32 s82, 33
	s_waitcnt vmcnt(0)
	s_barrier
	ds_read_b128 v[208:211], v244 offset:0
	ds_read_b128 v[212:215], v245 offset:0
	ds_read_b128 v[216:219], v246 offset:0
	ds_read_b128 v[220:223], v247 offset:0
	ds_read_b128 v[224:227], v244 offset:4096
	ds_read_b128 v[228:231], v245 offset:4096
	ds_read_b128 v[232:235], v246 offset:4096
	ds_read_b128 v[236:239], v247 offset:4096
	s_waitcnt lgkmcnt(7)
	v_mfma_f32_32x32x16_bf16 v[0:15], v[208:211], v[96:99], 0
	s_waitcnt lgkmcnt(6)
	v_mfma_f32_32x32x16_bf16 v[0:15], v[212:215], v[100:103], v[0:15]
	s_waitcnt lgkmcnt(5)
	v_mfma_f32_32x32x16_bf16 v[0:15], v[216:219], v[104:107], v[0:15]
	s_waitcnt lgkmcnt(4)
	v_mfma_f32_32x32x16_bf16 v[0:15], v[220:223], v[108:111], v[0:15]
	s_waitcnt lgkmcnt(0)
.Lat_loop:
	s_waitcnt lgkmcnt(4)
	s_cmp_lg_u32 s84, 0
	s_cbranch_scc1 .Lat_stab0
.Lat_stab0_ret:
	v_mfma_f32_32x32x16_bf16 v[16:31], v[224:227], v[96:99], 0
	ds_read_b128 v[208:211], v244 offset:16384
	v_cvt_pk_bf16_f32 v112, v80, v81
	v_cvt_pk_bf16_f32 v113, v82, v83
	v_cvt_pk_bf16_f32 v114, v84, v85
	v_cvt_pk_bf16_f32 v115, v86, v87
	v_cvt_pk_bf16_f32 v116, v88, v89
	v_mfma_f32_32x32x16_bf16 v[16:31], v[228:231], v[100:103], v[16:31]
	ds_read_b128 v[212:215], v245 offset:16384
	v_cvt_pk_bf16_f32 v117, v90, v91
	v_cvt_pk_bf16_f32 v118, v92, v93
	v_cvt_pk_bf16_f32 v119, v94, v95
	v_exp_f32_e32 v64, v0
	v_exp_f32_e32 v65, v1
	v_mfma_f32_32x32x16_bf16 v[16:31], v[232:235], v[104:107], v[16:31]
	ds_read_b128 v[216:219], v246 offset:16384
	v_exp_f32_e32 v66, v2
	v_add_f32_e32 v136, v64, v65
	v_exp_f32_e32 v67, v3
	v_add_f32_e32 v136, v66, v136
	v_exp_f32_e32 v68, v4
	v_mfma_f32_32x32x16_bf16 v[16:31], v[236:239], v[108:111], v[16:31]
	ds_read_b128 v[220:223], v247 offset:16384
	v_add_f32_e32 v136, v67, v136
	v_exp_f32_e32 v69, v5
	v_add_f32_e32 v136, v68, v136
	v_exp_f32_e32 v70, v6
	v_add_f32_e32 v136, v69, v136
	s_waitcnt lgkmcnt(4)
	v_mfma_f32_32x32x16_bf16 v[32:47], v[192:195], v[112:115], v[32:47]
	ds_read_b128 v[176:179], v248 offset:8192
	v_exp_f32_e32 v71, v7
	v_add_f32_e32 v136, v70, v136
	v_exp_f32_e32 v72, v8
	v_add_f32_e32 v136, v71, v136
	v_exp_f32_e32 v73, v9
	s_add_i32 m0, s83, 32768
	s_nop 0
	global_load_lds_dwordx4 v252, s[78:79]
	v_mfma_f32_32x32x16_bf16 v[48:63], v[196:199], v[112:115], v[48:63]
	ds_read_b128 v[180:183], v248 offset:12288
	v_add_f32_e32 v136, v72, v136
	v_exp_f32_e32 v74, v10
	v_add_f32_e32 v136, v73, v136
	v_exp_f32_e32 v75, v11
	v_add_f32_e32 v136, v74, v136
	global_load_lds_dwordx4 v253, s[78:79] offset:1024
	s_add_i32 m0, s83, 40960
	s_nop 0
	v_mfma_f32_32x32x16_bf16 v[32:47], v[200:203], v[116:119], v[32:47]
	ds_read_b128 v[184:187], v249 offset:8192
	v_exp_f32_e32 v76, v12
	v_add_f32_e32 v136, v75, v136
	v_exp_f32_e32 v77, v13
	v_add_f32_e32 v136, v76, v136
	v_exp_f32_e32 v78, v14
	global_load_lds_dwordx4 v254, s[80:81]
	s_add_u32 s78, s78, 0x2000
	s_addc_u32 s79, s79, 0
	v_mfma_f32_32x32x16_bf16 v[48:63], v[240:243], v[116:119], v[48:63]
	ds_read_b128 v[188:191], v249 offset:12288
	v_add_f32_e32 v136, v77, v136
	v_exp_f32_e32 v79, v15
	v_add_f32_e32 v136, v78, v136
	global_load_lds_dwordx4 v255, s[80:81] offset:1024
	s_add_u32 s80, s80, 0x80
	s_addc_u32 s81, s81, 0
	s_nop 0
	v_add_f32_e32 v134, v79, v136
	v_cmp_nge_f32_e32 vcc, s65, v134
	v_cmp_gt_f32_e64 s[0:1], s72, v134
	s_or_b64 vcc, vcc, s[0:1]
	s_cbranch_vccnz .Lat_rare0
.Lat_rare0_ret:
	v_add_f32_e32 v128, v128, v134
	s_waitcnt lgkmcnt(4)
	s_cmp_lg_u32 s84, 0
	s_cbranch_scc1 .Lat_stab1
.Lat_stab1_ret:
	v_mfma_f32_32x32x16_bf16 v[0:15], v[208:211], v[96:99], 0
	ds_read_b128 v[224:227], v244 offset:20480
	v_cvt_pk_bf16_f32 v112, v64, v65
	v_cvt_pk_bf16_f32 v113, v66, v67
	v_cvt_pk_bf16_f32 v114, v68, v69
	v_cvt_pk_bf16_f32 v115, v70, v71
	v_cvt_pk_bf16_f32 v116, v72, v73
	v_mfma_f32_32x32x16_bf16 v[0:15], v[212:215], v[100:103], v[0:15]
	ds_read_b128 v[228:231], v245 offset:20480
	v_cvt_pk_bf16_f32 v117, v74, v75
	v_cvt_pk_bf16_f32 v118, v76, v77
	v_cvt_pk_bf16_f32 v119, v78, v79
	v_exp_f32_e32 v80, v16
	v_exp_f32_e32 v81, v17
	v_mfma_f32_32x32x16_bf16 v[0:15], v[216:219], v[104:107], v[0:15]
	ds_read_b128 v[232:235], v246 offset:20480
	v_exp_f32_e32 v82, v18
	v_add_f32_e32 v136, v80, v81
	v_exp_f32_e32 v83, v19
	v_add_f32_e32 v136, v82, v136
	v_exp_f32_e32 v84, v20
	v_mfma_f32_32x32x16_bf16 v[0:15], v[220:223], v[108:111], v[0:15]
	ds_read_b128 v[236:239], v247 offset:20480
	v_add_f32_e32 v136, v83, v136
	v_exp_f32_e32 v85, v21
	v_add_f32_e32 v136, v84, v136
	v_exp_f32_e32 v86, v22
	v_add_f32_e32 v136, v85, v136
	s_waitcnt lgkmcnt(4)
	v_mfma_f32_32x32x16_bf16 v[32:47], v[176:179], v[112:115], v[32:47]
	ds_read_b128 v[192:195], v250 offset:8192
	v_exp_f32_e32 v87, v23
	v_add_f32_e32 v136, v86, v136
	v_exp_f32_e32 v88, v24
	v_add_f32_e32 v136, v87, v136
	v_exp_f32_e32 v89, v25
	v_mfma_f32_32x32x16_bf16 v[48:63], v[180:183], v[112:115], v[48:63]
	ds_read_b128 v[196:199], v250 offset:12288
	v_add_f32_e32 v136, v88, v136
	v_exp_f32_e32 v90, v26
	v_add_f32_e32 v136, v89, v136
	v_exp_f32_e32 v91, v27
	v_add_f32_e32 v136, v90, v136
	v_mfma_f32_32x32x16_bf16 v[32:47], v[184:187], v[116:119], v[32:47]
	ds_read_b128 v[200:203], v251 offset:8192
	v_exp_f32_e32 v92, v28
	v_add_f32_e32 v136, v91, v136
	v_exp_f32_e32 v93, v29
	v_add_f32_e32 v136, v92, v136
	v_exp_f32_e32 v94, v30
	v_mfma_f32_32x32x16_bf16 v[48:63], v[188:191], v[116:119], v[48:63]
	ds_read_b128 v[240:243], v251 offset:12288
	v_add_f32_e32 v136, v93, v136
	v_exp_f32_e32 v95, v31
	v_add_f32_e32 v136, v94, v136
	s_nop 0
	v_add_f32_e32 v134, v95, v136
	v_cmp_nge_f32_e32 vcc, s65, v134
	v_cmp_gt_f32_e64 s[0:1], s72, v134
	s_or_b64 vcc, vcc, s[0:1]
	s_cbranch_vccnz .Lat_rare1
.Lat_rare1_ret:
	v_add_f32_e32 v128, v128, v134
	s_waitcnt vmcnt(0)
	s_barrier
	s_waitcnt lgkmcnt(4)
	s_cmp_lg_u32 s84, 0
	s_cbranch_scc1 .Lat_stab2
.Lat_stab2_ret:
	v_mfma_f32_32x32x16_bf16 v[16:31], v[224:227], v[96:99], 0
	ds_read_b128 v[208:211], v244 offset:32768
	v_cvt_pk_bf16_f32 v112, v80, v81
	v_cvt_pk_bf16_f32 v113, v82, v83
	v_cvt_pk_bf16_f32 v114, v84, v85
	v_cvt_pk_bf16_f32 v115, v86, v87
	v_cvt_pk_bf16_f32 v116, v88, v89
	v_mfma_f32_32x32x16_bf16 v[16:31], v[228:231], v[100:103], v[16:31]
	ds_read_b128 v[212:215], v245 offset:32768
	v_cvt_pk_bf16_f32 v117, v90, v91
	v_cvt_pk_bf16_f32 v118, v92, v93
	v_cvt_pk_bf16_f32 v119, v94, v95
	v_exp_f32_e32 v64, v0
	v_exp_f32_e32 v65, v1
	v_mfma_f32_32x32x16_bf16 v[16:31], v[232:235], v[104:107], v[16:31]
	ds_read_b128 v[216:219], v246 offset:32768
	v_exp_f32_e32 v66, v2
	v_add_f32_e32 v136, v64, v65
	v_exp_f32_e32 v67, v3
	v_add_f32_e32 v136, v66, v136
	v_exp_f32_e32 v68, v4
	v_mfma_f32_32x32x16_bf16 v[16:31], v[236:239], v[108:111], v[16:31]
	ds_read_b128 v[220:223], v247 offset:32768
	v_add_f32_e32 v136, v67, v136
	v_exp_f32_e32 v69, v5
	v_add_f32_e32 v136, v68, v136
	v_exp_f32_e32 v70, v6
	v_add_f32_e32 v136, v69, v136
	s_waitcnt lgkmcnt(4)
	v_mfma_f32_32x32x16_bf16 v[32:47], v[192:195], v[112:115], v[32:47]
	ds_read_b128 v[176:179], v248 offset:24576
	v_exp_f32_e32 v71, v7
	v_add_f32_e32 v136, v70, v136
	v_exp_f32_e32 v72, v8
	v_add_f32_e32 v136, v71, v136
	v_exp_f32_e32 v73, v9
	s_add_i32 m0, s83, 49152
	s_nop 0
	global_load_lds_dwordx4 v252, s[78:79]
	v_mfma_f32_32x32x16_bf16 v[48:63], v[196:199], v[112:115], v[48:63]
	ds_read_b128 v[180:183], v248 offset:28672
	v_add_f32_e32 v136, v72, v136
	v_exp_f32_e32 v74, v10
	v_add_f32_e32 v136, v73, v136
	v_exp_f32_e32 v75, v11
	v_add_f32_e32 v136, v74, v136
	global_load_lds_dwordx4 v253, s[78:79] offset:1024
	s_add_i32 m0, s83, 57344
	s_nop 0
	v_mfma_f32_32x32x16_bf16 v[32:47], v[200:203], v[116:119], v[32:47]
	ds_read_b128 v[184:187], v249 offset:24576
	v_exp_f32_e32 v76, v12
	v_add_f32_e32 v136, v75, v136
	v_exp_f32_e32 v77, v13
	v_add_f32_e32 v136, v76, v136
	v_exp_f32_e32 v78, v14
	global_load_lds_dwordx4 v254, s[80:81]
	s_add_u32 s78, s78, 0x2000
	s_addc_u32 s79, s79, 0
	v_mfma_f32_32x32x16_bf16 v[48:63], v[240:243], v[116:119], v[48:63]
	ds_read_b128 v[188:191], v249 offset:28672
	v_add_f32_e32 v136, v77, v136
	v_exp_f32_e32 v79, v15
	v_add_f32_e32 v136, v78, v136
	global_load_lds_dwordx4 v255, s[80:81] offset:1024
	s_add_u32 s80, s80, 0x80
	s_addc_u32 s81, s81, 0
	s_nop 0
	v_add_f32_e32 v134, v79, v136
	v_cmp_nge_f32_e32 vcc, s65, v134
	v_cmp_gt_f32_e64 s[0:1], s72, v134
	s_or_b64 vcc, vcc, s[0:1]
	s_cbranch_vccnz .Lat_rare2

.Lat_stab3_ret:
	v_mfma_f32_32x32x16_bf16 v[0:15], v[208:211], v[96:99], 0
	ds_read_b128 v[224:227], v244 offset:36864
	v_cvt_pk_bf16_f32 v112, v64, v65
	v_cvt_pk_bf16_f32 v113, v66, v67
	v_cvt_pk_bf16_f32 v114, v68, v69
	v_cvt_pk_bf16_f32 v115, v70, v71
	v_cvt_pk_bf16_f32 v116, v72, v73
	v_mfma_f32_32x32x16_bf16 v[0:15], v[212:215], v[100:103], v[0:15]
	ds_read_b128 v[228:231], v245 offset:36864
	v_cvt_pk_bf16_f32 v117, v74, v75
	v_cvt_pk_bf16_f32 v118, v76, v77
	v_cvt_pk_bf16_f32 v119, v78, v79
	v_exp_f32_e32 v80, v16
	v_exp_f32_e32 v81, v17
	v_mfma_f32_32x32x16_bf16 v[0:15], v[216:219], v[104:107], v[0:15]
	ds_read_b128 v[232:235], v246 offset:36864
	v_exp_f32_e32 v82, v18
	v_add_f32_e32 v136, v80, v81
	v_exp_f32_e32 v83, v19
	v_add_f32_e32 v136, v82, v136
	v_exp_f32_e32 v84, v20
	v_mfma_f32_32x32x16_bf16 v[0:15], v[220:223], v[108:111], v[0:15]
	ds_read_b128 v[236:239], v247 offset:36864
	v_add_f32_e32 v136, v83, v136
	v_exp_f32_e32 v85, v21
	v_add_f32_e32 v136, v84, v136
	v_exp_f32_e32 v86, v22
	v_add_f32_e32 v136, v85, v136
	s_waitcnt lgkmcnt(4)
	v_mfma_f32_32x32x16_bf16 v[32:47], v[176:179], v[112:115], v[32:47]
	ds_read_b128 v[192:195], v250 offset:24576
	v_exp_f32_e32 v87, v23
	v_add_f32_e32 v136, v86, v136
	v_exp_f32_e32 v88, v24
	v_add_f32_e32 v136, v87, v136
	v_exp_f32_e32 v89, v25
	v_mfma_f32_32x32x16_bf16 v[48:63], v[180:183], v[112:115], v[48:63]
	ds_read_b128 v[196:199], v250 offset:28672
	v_add_f32_e32 v136, v88, v136
	v_exp_f32_e32 v90, v26
	v_add_f32_e32 v136, v89, v136
	v_exp_f32_e32 v91, v27
	v_add_f32_e32 v136, v90, v136
	v_mfma_f32_32x32x16_bf16 v[32:47], v[184:187], v[116:119], v[32:47]
	ds_read_b128 v[200:203], v251 offset:24576
	v_exp_f32_e32 v92, v28
	v_add_f32_e32 v136, v91, v136
	v_exp_f32_e32 v93, v29
	v_add_f32_e32 v136, v92, v136
	v_exp_f32_e32 v94, v30
	v_mfma_f32_32x32x16_bf16 v[48:63], v[188:191], v[116:119], v[48:63]
	ds_read_b128 v[240:243], v251 offset:28672
	v_add_f32_e32 v136, v93, v136
	v_exp_f32_e32 v95, v31
	v_add_f32_e32 v136, v94, v136
	s_nop 0
	v_add_f32_e32 v134, v95, v136
	v_cmp_nge_f32_e32 vcc, s65, v134
	v_cmp_gt_f32_e64 s[0:1], s72, v134
	s_or_b64 vcc, vcc, s[0:1]
	s_cbranch_vccnz .Lat_rare3

.Lat_stab4_ret:
	v_mfma_f32_32x32x16_bf16 v[16:31], v[224:227], v[96:99], 0
	ds_read_b128 v[208:211], v244 offset:49152
	v_cvt_pk_bf16_f32 v112, v80, v81
	v_cvt_pk_bf16_f32 v113, v82, v83
	v_cvt_pk_bf16_f32 v114, v84, v85
	v_cvt_pk_bf16_f32 v115, v86, v87
	v_cvt_pk_bf16_f32 v116, v88, v89
	v_mfma_f32_32x32x16_bf16 v[16:31], v[228:231], v[100:103], v[16:31]
	ds_read_b128 v[212:215], v245 offset:49152
	v_cvt_pk_bf16_f32 v117, v90, v91
	v_cvt_pk_bf16_f32 v118, v92, v93
	v_cvt_pk_bf16_f32 v119, v94, v95
	v_exp_f32_e32 v64, v0
	v_exp_f32_e32 v65, v1
	v_mfma_f32_32x32x16_bf16 v[16:31], v[232:235], v[104:107], v[16:31]
	ds_read_b128 v[216:219], v246 offset:49152
	v_exp_f32_e32 v66, v2
	v_add_f32_e32 v136, v64, v65
	v_exp_f32_e32 v67, v3
	v_add_f32_e32 v136, v66, v136
	v_exp_f32_e32 v68, v4
	v_mfma_f32_32x32x16_bf16 v[16:31], v[236:239], v[108:111], v[16:31]
	ds_read_b128 v[220:223], v247 offset:49152
	v_add_f32_e32 v136, v67, v136
	v_exp_f32_e32 v69, v5
	v_add_f32_e32 v136, v68, v136
	v_exp_f32_e32 v70, v6
	v_add_f32_e32 v136, v69, v136
	s_waitcnt lgkmcnt(4)
	v_mfma_f32_32x32x16_bf16 v[32:47], v[192:195], v[112:115], v[32:47]
	ds_read_b128 v[176:179], v248 offset:40960
	v_exp_f32_e32 v71, v7
	v_add_f32_e32 v136, v70, v136
	v_exp_f32_e32 v72, v8
	v_add_f32_e32 v136, v71, v136
	v_exp_f32_e32 v73, v9
	s_add_i32 m0, s83, 0
	s_nop 0
	global_load_lds_dwordx4 v252, s[78:79]
	v_mfma_f32_32x32x16_bf16 v[48:63], v[196:199], v[112:115], v[48:63]
	ds_read_b128 v[180:183], v248 offset:45056
	v_add_f32_e32 v136, v72, v136
	v_exp_f32_e32 v74, v10
	v_add_f32_e32 v136, v73, v136
	v_exp_f32_e32 v75, v11
	v_add_f32_e32 v136, v74, v136
	global_load_lds_dwordx4 v253, s[78:79] offset:1024
	s_add_i32 m0, s83, 8192
	s_nop 0
	v_mfma_f32_32x32x16_bf16 v[32:47], v[200:203], v[116:119], v[32:47]
	ds_read_b128 v[184:187], v249 offset:40960
	v_exp_f32_e32 v76, v12
	v_add_f32_e32 v136, v75, v136
	v_exp_f32_e32 v77, v13
	v_add_f32_e32 v136, v76, v136
	v_exp_f32_e32 v78, v14
	global_load_lds_dwordx4 v254, s[80:81]
	s_add_u32 s78, s78, 0x2000
	s_addc_u32 s79, s79, 0
	v_mfma_f32_32x32x16_bf16 v[48:63], v[240:243], v[116:119], v[48:63]
	ds_read_b128 v[188:191], v249 offset:45056
	v_add_f32_e32 v136, v77, v136
	v_exp_f32_e32 v79, v15
	v_add_f32_e32 v136, v78, v136
	global_load_lds_dwordx4 v255, s[80:81] offset:1024
	s_add_u32 s80, s80, 0x80
	s_addc_u32 s81, s81, 0
	s_nop 0
	v_add_f32_e32 v134, v79, v136
	v_cmp_nge_f32_e32 vcc, s65, v134
	v_cmp_gt_f32_e64 s[0:1], s72, v134
	s_or_b64 vcc, vcc, s[0:1]
	s_cbranch_vccnz .Lat_rare4

.Lat_stab5_ret:
	v_mfma_f32_32x32x16_bf16 v[0:15], v[208:211], v[96:99], 0
	ds_read_b128 v[224:227], v244 offset:53248
	v_cvt_pk_bf16_f32 v112, v64, v65
	v_cvt_pk_bf16_f32 v113, v66, v67
	v_cvt_pk_bf16_f32 v114, v68, v69
	v_cvt_pk_bf16_f32 v115, v70, v71
	v_cvt_pk_bf16_f32 v116, v72, v73
	v_mfma_f32_32x32x16_bf16 v[0:15], v[212:215], v[100:103], v[0:15]
	ds_read_b128 v[228:231], v245 offset:53248
	v_cvt_pk_bf16_f32 v117, v74, v75
	v_cvt_pk_bf16_f32 v118, v76, v77
	v_cvt_pk_bf16_f32 v119, v78, v79
	v_exp_f32_e32 v80, v16
	v_exp_f32_e32 v81, v17
	v_mfma_f32_32x32x16_bf16 v[0:15], v[216:219], v[104:107], v[0:15]
	ds_read_b128 v[232:235], v246 offset:53248
	v_exp_f32_e32 v82, v18
	v_add_f32_e32 v136, v80, v81
	v_exp_f32_e32 v83, v19
	v_add_f32_e32 v136, v82, v136
	v_exp_f32_e32 v84, v20
	v_mfma_f32_32x32x16_bf16 v[0:15], v[220:223], v[108:111], v[0:15]
	ds_read_b128 v[236:239], v247 offset:53248
	v_add_f32_e32 v136, v83, v136
	v_exp_f32_e32 v85, v21
	v_add_f32_e32 v136, v84, v136
	v_exp_f32_e32 v86, v22
	v_add_f32_e32 v136, v85, v136
	s_waitcnt lgkmcnt(4)
	v_mfma_f32_32x32x16_bf16 v[32:47], v[176:179], v[112:115], v[32:47]
	ds_read_b128 v[192:195], v250 offset:40960
	v_exp_f32_e32 v87, v23
	v_add_f32_e32 v136, v86, v136
	v_exp_f32_e32 v88, v24
	v_add_f32_e32 v136, v87, v136
	v_exp_f32_e32 v89, v25
	v_mfma_f32_32x32x16_bf16 v[48:63], v[180:183], v[112:115], v[48:63]
	ds_read_b128 v[196:199], v250 offset:45056
	v_add_f32_e32 v136, v88, v136
	v_exp_f32_e32 v90, v26
	v_add_f32_e32 v136, v89, v136
	v_exp_f32_e32 v91, v27
	v_add_f32_e32 v136, v90, v136
	v_mfma_f32_32x32x16_bf16 v[32:47], v[184:187], v[116:119], v[32:47]
	ds_read_b128 v[200:203], v251 offset:40960
	v_exp_f32_e32 v92, v28
	v_add_f32_e32 v136, v91, v136
	v_exp_f32_e32 v93, v29
	v_add_f32_e32 v136, v92, v136
	v_exp_f32_e32 v94, v30
	v_mfma_f32_32x32x16_bf16 v[48:63], v[188:191], v[116:119], v[48:63]
	ds_read_b128 v[240:243], v251 offset:45056
	v_add_f32_e32 v136, v93, v136
	v_exp_f32_e32 v95, v31
	v_add_f32_e32 v136, v94, v136
	s_nop 0
	v_add_f32_e32 v134, v95, v136
	v_cmp_nge_f32_e32 vcc, s65, v134
	v_cmp_gt_f32_e64 s[0:1], s72, v134
	s_or_b64 vcc, vcc, s[0:1]
	s_cbranch_vccnz .Lat_rare5

.Lat_stab6_ret:
	v_mfma_f32_32x32x16_bf16 v[16:31], v[224:227], v[96:99], 0
	ds_read_b128 v[208:211], v244 offset:0
	v_cvt_pk_bf16_f32 v112, v80, v81
	v_cvt_pk_bf16_f32 v113, v82, v83
	v_cvt_pk_bf16_f32 v114, v84, v85
	v_cvt_pk_bf16_f32 v115, v86, v87
	v_cvt_pk_bf16_f32 v116, v88, v89
	v_mfma_f32_32x32x16_bf16 v[16:31], v[228:231], v[100:103], v[16:31]
	ds_read_b128 v[212:215], v245 offset:0
	v_cvt_pk_bf16_f32 v117, v90, v91
	v_cvt_pk_bf16_f32 v118, v92, v93
	v_cvt_pk_bf16_f32 v119, v94, v95
	v_exp_f32_e32 v64, v0
	v_exp_f32_e32 v65, v1
	v_mfma_f32_32x32x16_bf16 v[16:31], v[232:235], v[104:107], v[16:31]
	ds_read_b128 v[216:219], v246 offset:0
	v_exp_f32_e32 v66, v2
	v_add_f32_e32 v136, v64, v65
	v_exp_f32_e32 v67, v3
	v_add_f32_e32 v136, v66, v136
	v_exp_f32_e32 v68, v4
	v_mfma_f32_32x32x16_bf16 v[16:31], v[236:239], v[108:111], v[16:31]
	ds_read_b128 v[220:223], v247 offset:0
	v_add_f32_e32 v136, v67, v136
	v_exp_f32_e32 v69, v5
	v_add_f32_e32 v136, v68, v136
	v_exp_f32_e32 v70, v6
	v_add_f32_e32 v136, v69, v136
	s_waitcnt lgkmcnt(4)
	v_mfma_f32_32x32x16_bf16 v[32:47], v[192:195], v[112:115], v[32:47]
	ds_read_b128 v[176:179], v248 offset:57344
	v_exp_f32_e32 v71, v7
	v_add_f32_e32 v136, v70, v136
	v_exp_f32_e32 v72, v8
	v_add_f32_e32 v136, v71, v136
	v_exp_f32_e32 v73, v9
	s_add_i32 m0, s83, 16384
	s_nop 0
	global_load_lds_dwordx4 v252, s[78:79]
	v_mfma_f32_32x32x16_bf16 v[48:63], v[196:199], v[112:115], v[48:63]
	ds_read_b128 v[180:183], v248 offset:61440
	v_add_f32_e32 v136, v72, v136
	v_exp_f32_e32 v74, v10
	v_add_f32_e32 v136, v73, v136
	v_exp_f32_e32 v75, v11
	v_add_f32_e32 v136, v74, v136
	global_load_lds_dwordx4 v253, s[78:79] offset:1024
	s_add_i32 m0, s83, 24576
	s_nop 0
	v_mfma_f32_32x32x16_bf16 v[32:47], v[200:203], v[116:119], v[32:47]
	ds_read_b128 v[184:187], v249 offset:57344
	v_exp_f32_e32 v76, v12
	v_add_f32_e32 v136, v75, v136
	v_exp_f32_e32 v77, v13
	v_add_f32_e32 v136, v76, v136
	v_exp_f32_e32 v78, v14
	global_load_lds_dwordx4 v254, s[80:81]
	s_add_u32 s78, s78, 0x2000
	s_addc_u32 s79, s79, 0
	v_mfma_f32_32x32x16_bf16 v[48:63], v[240:243], v[116:119], v[48:63]
	ds_read_b128 v[188:191], v249 offset:61440
	v_add_f32_e32 v136, v77, v136
	v_exp_f32_e32 v79, v15
	v_add_f32_e32 v136, v78, v136
	global_load_lds_dwordx4 v255, s[80:81] offset:1024
	s_add_u32 s80, s80, 0x80
	s_addc_u32 s81, s81, 0
	s_nop 0
	v_add_f32_e32 v134, v79, v136
	v_cmp_nge_f32_e32 vcc, s65, v134
	v_cmp_gt_f32_e64 s[0:1], s72, v134
	s_or_b64 vcc, vcc, s[0:1]
	s_cbranch_vccnz .Lat_rare6

.Lat_stab7_ret:
	v_mfma_f32_32x32x16_bf16 v[0:15], v[208:211], v[96:99], 0
	ds_read_b128 v[224:227], v244 offset:4096
	v_cvt_pk_bf16_f32 v112, v64, v65
	v_cvt_pk_bf16_f32 v113, v66, v67
	v_cvt_pk_bf16_f32 v114, v68, v69
	v_cvt_pk_bf16_f32 v115, v70, v71
	v_cvt_pk_bf16_f32 v116, v72, v73
	v_mfma_f32_32x32x16_bf16 v[0:15], v[212:215], v[100:103], v[0:15]
	ds_read_b128 v[228:231], v245 offset:4096
	v_cvt_pk_bf16_f32 v117, v74, v75
	v_cvt_pk_bf16_f32 v118, v76, v77
	v_cvt_pk_bf16_f32 v119, v78, v79
	v_exp_f32_e32 v80, v16
	v_exp_f32_e32 v81, v17
	v_mfma_f32_32x32x16_bf16 v[0:15], v[216:219], v[104:107], v[0:15]
	ds_read_b128 v[232:235], v246 offset:4096
	v_exp_f32_e32 v82, v18
	v_add_f32_e32 v136, v80, v81
	v_exp_f32_e32 v83, v19
	v_add_f32_e32 v136, v82, v136
	v_exp_f32_e32 v84, v20
	v_mfma_f32_32x32x16_bf16 v[0:15], v[220:223], v[108:111], v[0:15]
	ds_read_b128 v[236:239], v247 offset:4096
	v_add_f32_e32 v136, v83, v136
	v_exp_f32_e32 v85, v21
	v_add_f32_e32 v136, v84, v136
	v_exp_f32_e32 v86, v22
	v_add_f32_e32 v136, v85, v136
	s_waitcnt lgkmcnt(4)
	v_mfma_f32_32x32x16_bf16 v[32:47], v[176:179], v[112:115], v[32:47]
	ds_read_b128 v[192:195], v250 offset:57344
	v_exp_f32_e32 v87, v23
	v_add_f32_e32 v136, v86, v136
	v_exp_f32_e32 v88, v24
	v_add_f32_e32 v136, v87, v136
	v_exp_f32_e32 v89, v25
	v_mfma_f32_32x32x16_bf16 v[48:63], v[180:183], v[112:115], v[48:63]
	ds_read_b128 v[196:199], v250 offset:61440
	v_add_f32_e32 v136, v88, v136
	v_exp_f32_e32 v90, v26
	v_add_f32_e32 v136, v89, v136
	v_exp_f32_e32 v91, v27
	v_add_f32_e32 v136, v90, v136
	v_mfma_f32_32x32x16_bf16 v[32:47], v[184:187], v[116:119], v[32:47]
	ds_read_b128 v[200:203], v251 offset:57344
	v_exp_f32_e32 v92, v28
	v_add_f32_e32 v136, v91, v136
	v_exp_f32_e32 v93, v29
	v_add_f32_e32 v136, v92, v136
	v_exp_f32_e32 v94, v30
	v_mfma_f32_32x32x16_bf16 v[48:63], v[188:191], v[116:119], v[48:63]
	ds_read_b128 v[240:243], v251 offset:61440
	v_add_f32_e32 v136, v93, v136
	v_exp_f32_e32 v95, v31
	v_add_f32_e32 v136, v94, v136
	s_nop 0
	v_add_f32_e32 v134, v95, v136
	v_cmp_nge_f32_e32 vcc, s65, v134
	v_cmp_gt_f32_e64 s[0:1], s72, v134
	s_or_b64 vcc, vcc, s[0:1]
	s_cbranch_vccnz .Lat_rare7
.Lat_rare7_ret:
	v_add_f32_e32 v128, v128, v134
	s_waitcnt vmcnt(0)
	s_barrier
	s_sub_u32 s82, s82, 1
	s_cmp_lg_u32 s82, 0
	s_cbranch_scc1 .Lat_loop
	v_cvt_pk_bf16_f32 v112, v80, v81
	v_cvt_pk_bf16_f32 v113, v82, v83
	v_cvt_pk_bf16_f32 v114, v84, v85
	v_cvt_pk_bf16_f32 v115, v86, v87
	v_cvt_pk_bf16_f32 v116, v88, v89
	v_cvt_pk_bf16_f32 v117, v90, v91
	v_cvt_pk_bf16_f32 v118, v92, v93
	v_cvt_pk_bf16_f32 v119, v94, v95
	s_waitcnt lgkmcnt(0)
	v_mfma_f32_32x32x16_bf16 v[32:47], v[192:195], v[112:115], v[32:47]
	v_mfma_f32_32x32x16_bf16 v[48:63], v[196:199], v[112:115], v[48:63]
	v_mfma_f32_32x32x16_bf16 v[32:47], v[200:203], v[116:119], v[32:47]
	v_mfma_f32_32x32x16_bf16 v[48:63], v[240:243], v[116:119], v[48:63]
	s_nop 7
	s_nop 7
	s_waitcnt vmcnt(0)
	s_lshr_b32 s0, s2, 8
	s_lshl_b32 s0, s0, 13
	s_and_b32 s1, s2, 63
	s_lshl_b32 s1, s1, 7
	s_or_b32 s0, s0, s1
	s_bfe_u32 s1, s2, 0x20006
	s_lshl_b32 s1, s1, 7
	s_add_u32 s86, s94, 0x3200000
	s_addc_u32 s87, s95, 0
	s_add_u32 s88, s94, 0x1100200
	s_addc_u32 s89, s95, 0
	v_lshrrev_b32_e32 v0, 1, v138
	v_and_b32_e32 v0, 0xe0, v0
	v_and_or_b32 v0, v138, 31, v0
	v_add_u32_e32 v0, s0, v0
	v_bfe_u32 v3, v138, 5, 1
	v_lshl_add_u32 v3, v3, 3, s1
	v_mul_lo_u32 v1, v0, s64
	v_add_u32_e32 v1, v1, v3
	v_lshl_add_u32 v2, v0, 11, v3
	global_load_dwordx2 v[64:65], v1, s[86:87]
	global_load_dwordx2 v[66:67], v1, s[86:87] offset:16
	global_load_dwordx2 v[68:69], v1, s[86:87] offset:32
	global_load_dwordx2 v[70:71], v1, s[86:87] offset:48
	global_load_dwordx2 v[72:73], v1, s[86:87] offset:64
	global_load_dwordx2 v[74:75], v1, s[86:87] offset:80
	global_load_dwordx2 v[76:77], v1, s[86:87] offset:96
	global_load_dwordx2 v[78:79], v1, s[86:87] offset:112
	v_mbcnt_lo_u32_b32 v4, -1, 0
	v_mbcnt_hi_u32_b32 v4, -1, v4
	v_xor_b32_e32 v4, 32, v4
	v_lshlrev_b32_e32 v4, 2, v4
	ds_bpermute_b32 v5, v4, v128
	s_waitcnt lgkmcnt(0)
	v_add_f32_e32 v5, v128, v5
	v_mov_b32_e32 v7, 1.0
	v_div_scale_f32 v8, s[0:1], v5, v5, v7
	v_rcp_f32_e32 v9, v8
	s_nop 0
	v_fma_f32 v10, -v8, v9, 1.0
	v_fmac_f32_e32 v9, v10, v9
	v_div_scale_f32 v10, vcc, v7, v5, v7
	v_mul_f32_e32 v11, v10, v9
	v_fma_f32 v12, -v8, v11, v10
	v_fmac_f32_e32 v11, v12, v9
	v_fma_f32 v8, -v8, v11, v10
	v_div_fmas_f32 v8, v8, v9, v11
	v_div_fixup_f32 v6, v8, v5, v7
	s_waitcnt vmcnt(7)
	v_lshlrev_b32_e32 v16, 16, v64
	v_and_b32_e32 v17, 0xffff0000, v64
	v_lshlrev_b32_e32 v18, 16, v65
	v_and_b32_e32 v19, 0xffff0000, v65
	v_mul_f32_e32 v20, 0xbfb8aa3b, v16
	v_mul_f32_e32 v21, 0xbfb8aa3b, v17
	v_mul_f32_e32 v22, 0xbfb8aa3b, v18
	v_mul_f32_e32 v23, 0xbfb8aa3b, v19
	v_exp_f32_e32 v20, v20
	v_exp_f32_e32 v21, v21
	v_exp_f32_e32 v22, v22
	v_exp_f32_e32 v23, v23
	s_nop 0
	v_add_f32_e32 v20, 1.0, v20
	v_add_f32_e32 v21, 1.0, v21
	v_add_f32_e32 v22, 1.0, v22
	v_add_f32_e32 v23, 1.0, v23
	v_div_scale_f32 v8, s[0:1], v20, v20, v16
	v_rcp_f32_e32 v9, v8
	s_nop 0
	v_fma_f32 v10, -v8, v9, 1.0
	v_fmac_f32_e32 v9, v10, v9
	v_div_scale_f32 v10, vcc, v16, v20, v16
	v_mul_f32_e32 v11, v10, v9
	v_fma_f32 v12, -v8, v11, v10
	v_fmac_f32_e32 v11, v12, v9
	v_fma_f32 v8, -v8, v11, v10
	v_div_fmas_f32 v8, v8, v9, v11
	v_div_fixup_f32 v24, v8, v20, v16
	v_div_scale_f32 v8, s[0:1], v21, v21, v17
	v_rcp_f32_e32 v9, v8
	s_nop 0
	v_fma_f32 v10, -v8, v9, 1.0
	v_fmac_f32_e32 v9, v10, v9
	v_div_scale_f32 v10, vcc, v17, v21, v17
	v_mul_f32_e32 v11, v10, v9
	v_fma_f32 v12, -v8, v11, v10
	v_fmac_f32_e32 v11, v12, v9
	v_fma_f32 v8, -v8, v11, v10
	v_div_fmas_f32 v8, v8, v9, v11
	v_div_fixup_f32 v25, v8, v21, v17
	v_div_scale_f32 v8, s[0:1], v22, v22, v18
	v_rcp_f32_e32 v9, v8
	s_nop 0
	v_fma_f32 v10, -v8, v9, 1.0
	v_fmac_f32_e32 v9, v10, v9
	v_div_scale_f32 v10, vcc, v18, v22, v18
	v_mul_f32_e32 v11, v10, v9
	v_fma_f32 v12, -v8, v11, v10
	v_fmac_f32_e32 v11, v12, v9
	v_fma_f32 v8, -v8, v11, v10
	v_div_fmas_f32 v8, v8, v9, v11
	v_div_fixup_f32 v26, v8, v22, v18
	v_div_scale_f32 v8, s[0:1], v23, v23, v19
	v_rcp_f32_e32 v9, v8
	s_nop 0
	v_fma_f32 v10, -v8, v9, 1.0
	v_fmac_f32_e32 v9, v10, v9
	v_div_scale_f32 v10, vcc, v19, v23, v19
	v_mul_f32_e32 v11, v10, v9
	v_fma_f32 v12, -v8, v11, v10
	v_fmac_f32_e32 v11, v12, v9
	v_fma_f32 v8, -v8, v11, v10
	v_div_fmas_f32 v8, v8, v9, v11
	v_div_fixup_f32 v27, v8, v23, v19
	v_mul_f32_e32 v24, v24, v32
	v_mul_f32_e32 v25, v25, v33
	v_mul_f32_e32 v26, v26, v34
	v_mul_f32_e32 v27, v27, v35
	v_mul_f32_e32 v24, v24, v6
	v_mul_f32_e32 v25, v25, v6
	v_mul_f32_e32 v26, v26, v6
	v_mul_f32_e32 v27, v27, v6
	v_cvt_pk_bf16_f32 v28, v24, v25
	v_cvt_pk_bf16_f32 v29, v26, v27
	global_store_dwordx2 v2, v[28:29], s[88:89]
	s_waitcnt vmcnt(7)
	v_lshlrev_b32_e32 v16, 16, v66
	v_and_b32_e32 v17, 0xffff0000, v66
	v_lshlrev_b32_e32 v18, 16, v67
	v_and_b32_e32 v19, 0xffff0000, v67
	v_mul_f32_e32 v20, 0xbfb8aa3b, v16
	v_mul_f32_e32 v21, 0xbfb8aa3b, v17
	v_mul_f32_e32 v22, 0xbfb8aa3b, v18
	v_mul_f32_e32 v23, 0xbfb8aa3b, v19
	v_exp_f32_e32 v20, v20
	v_exp_f32_e32 v21, v21
	v_exp_f32_e32 v22, v22
	v_exp_f32_e32 v23, v23
	s_nop 0
	v_add_f32_e32 v20, 1.0, v20
	v_add_f32_e32 v21, 1.0, v21
	v_add_f32_e32 v22, 1.0, v22
	v_add_f32_e32 v23, 1.0, v23
	v_div_scale_f32 v8, s[0:1], v20, v20, v16
	v_rcp_f32_e32 v9, v8
	s_nop 0
	v_fma_f32 v10, -v8, v9, 1.0
	v_fmac_f32_e32 v9, v10, v9
	v_div_scale_f32 v10, vcc, v16, v20, v16
	v_mul_f32_e32 v11, v10, v9
	v_fma_f32 v12, -v8, v11, v10
	v_fmac_f32_e32 v11, v12, v9
	v_fma_f32 v8, -v8, v11, v10
	v_div_fmas_f32 v8, v8, v9, v11
	v_div_fixup_f32 v24, v8, v20, v16
	v_div_scale_f32 v8, s[0:1], v21, v21, v17
	v_rcp_f32_e32 v9, v8
	s_nop 0
	v_fma_f32 v10, -v8, v9, 1.0
	v_fmac_f32_e32 v9, v10, v9
	v_div_scale_f32 v10, vcc, v17, v21, v17
	v_mul_f32_e32 v11, v10, v9
	v_fma_f32 v12, -v8, v11, v10
	v_fmac_f32_e32 v11, v12, v9
	v_fma_f32 v8, -v8, v11, v10
	v_div_fmas_f32 v8, v8, v9, v11
	v_div_fixup_f32 v25, v8, v21, v17
	v_div_scale_f32 v8, s[0:1], v22, v22, v18
	v_rcp_f32_e32 v9, v8
	s_nop 0
	v_fma_f32 v10, -v8, v9, 1.0
	v_fmac_f32_e32 v9, v10, v9
	v_div_scale_f32 v10, vcc, v18, v22, v18
	v_mul_f32_e32 v11, v10, v9
	v_fma_f32 v12, -v8, v11, v10
	v_fmac_f32_e32 v11, v12, v9
	v_fma_f32 v8, -v8, v11, v10
	v_div_fmas_f32 v8, v8, v9, v11
	v_div_fixup_f32 v26, v8, v22, v18
	v_div_scale_f32 v8, s[0:1], v23, v23, v19
	v_rcp_f32_e32 v9, v8
	s_nop 0
	v_fma_f32 v10, -v8, v9, 1.0
	v_fmac_f32_e32 v9, v10, v9
	v_div_scale_f32 v10, vcc, v19, v23, v19
	v_mul_f32_e32 v11, v10, v9
	v_fma_f32 v12, -v8, v11, v10
	v_fmac_f32_e32 v11, v12, v9
	v_fma_f32 v8, -v8, v11, v10
	v_div_fmas_f32 v8, v8, v9, v11
	v_div_fixup_f32 v27, v8, v23, v19
	v_mul_f32_e32 v24, v24, v36
	v_mul_f32_e32 v25, v25, v37
	v_mul_f32_e32 v26, v26, v38
	v_mul_f32_e32 v27, v27, v39
	v_mul_f32_e32 v24, v24, v6
	v_mul_f32_e32 v25, v25, v6
	v_mul_f32_e32 v26, v26, v6
	v_mul_f32_e32 v27, v27, v6
	v_cvt_pk_bf16_f32 v30, v24, v25
	v_cvt_pk_bf16_f32 v31, v26, v27
	global_store_dwordx2 v2, v[30:31], s[88:89] offset:16
	s_waitcnt vmcnt(7)
	v_lshlrev_b32_e32 v16, 16, v68
	v_and_b32_e32 v17, 0xffff0000, v68
	v_lshlrev_b32_e32 v18, 16, v69
	v_and_b32_e32 v19, 0xffff0000, v69
	v_mul_f32_e32 v20, 0xbfb8aa3b, v16
	v_mul_f32_e32 v21, 0xbfb8aa3b, v17
	v_mul_f32_e32 v22, 0xbfb8aa3b, v18
	v_mul_f32_e32 v23, 0xbfb8aa3b, v19
	v_exp_f32_e32 v20, v20
	v_exp_f32_e32 v21, v21
	v_exp_f32_e32 v22, v22
	v_exp_f32_e32 v23, v23
	s_nop 0
	v_add_f32_e32 v20, 1.0, v20
	v_add_f32_e32 v21, 1.0, v21
	v_add_f32_e32 v22, 1.0, v22
	v_add_f32_e32 v23, 1.0, v23
	v_div_scale_f32 v8, s[0:1], v20, v20, v16
	v_rcp_f32_e32 v9, v8
	s_nop 0
	v_fma_f32 v10, -v8, v9, 1.0
	v_fmac_f32_e32 v9, v10, v9
	v_div_scale_f32 v10, vcc, v16, v20, v16
	v_mul_f32_e32 v11, v10, v9
	v_fma_f32 v12, -v8, v11, v10
	v_fmac_f32_e32 v11, v12, v9
	v_fma_f32 v8, -v8, v11, v10
	v_div_fmas_f32 v8, v8, v9, v11
	v_div_fixup_f32 v24, v8, v20, v16
	v_div_scale_f32 v8, s[0:1], v21, v21, v17
	v_rcp_f32_e32 v9, v8
	s_nop 0
	v_fma_f32 v10, -v8, v9, 1.0
	v_fmac_f32_e32 v9, v10, v9
	v_div_scale_f32 v10, vcc, v17, v21, v17
	v_mul_f32_e32 v11, v10, v9
	v_fma_f32 v12, -v8, v11, v10
	v_fmac_f32_e32 v11, v12, v9
	v_fma_f32 v8, -v8, v11, v10
	v_div_fmas_f32 v8, v8, v9, v11
	v_div_fixup_f32 v25, v8, v21, v17
	v_div_scale_f32 v8, s[0:1], v22, v22, v18
	v_rcp_f32_e32 v9, v8
	s_nop 0
	v_fma_f32 v10, -v8, v9, 1.0
	v_fmac_f32_e32 v9, v10, v9
	v_div_scale_f32 v10, vcc, v18, v22, v18
	v_mul_f32_e32 v11, v10, v9
	v_fma_f32 v12, -v8, v11, v10
	v_fmac_f32_e32 v11, v12, v9
	v_fma_f32 v8, -v8, v11, v10
	v_div_fmas_f32 v8, v8, v9, v11
	v_div_fixup_f32 v26, v8, v22, v18
	v_div_scale_f32 v8, s[0:1], v23, v23, v19
	v_rcp_f32_e32 v9, v8
	s_nop 0
	v_fma_f32 v10, -v8, v9, 1.0
	v_fmac_f32_e32 v9, v10, v9
	v_div_scale_f32 v10, vcc, v19, v23, v19
	v_mul_f32_e32 v11, v10, v9
	v_fma_f32 v12, -v8, v11, v10
	v_fmac_f32_e32 v11, v12, v9
	v_fma_f32 v8, -v8, v11, v10
	v_div_fmas_f32 v8, v8, v9, v11
	v_div_fixup_f32 v27, v8, v23, v19
	v_mul_f32_e32 v24, v24, v40
	v_mul_f32_e32 v25, v25, v41
	v_mul_f32_e32 v26, v26, v42
	v_mul_f32_e32 v27, v27, v43
	v_mul_f32_e32 v24, v24, v6
	v_mul_f32_e32 v25, v25, v6
	v_mul_f32_e32 v26, v26, v6
	v_mul_f32_e32 v27, v27, v6
	v_cvt_pk_bf16_f32 v28, v24, v25
	v_cvt_pk_bf16_f32 v29, v26, v27
	global_store_dwordx2 v2, v[28:29], s[88:89] offset:32
	s_waitcnt vmcnt(7)
	v_lshlrev_b32_e32 v16, 16, v70
	v_and_b32_e32 v17, 0xffff0000, v70
	v_lshlrev_b32_e32 v18, 16, v71
	v_and_b32_e32 v19, 0xffff0000, v71
	v_mul_f32_e32 v20, 0xbfb8aa3b, v16
	v_mul_f32_e32 v21, 0xbfb8aa3b, v17
	v_mul_f32_e32 v22, 0xbfb8aa3b, v18
	v_mul_f32_e32 v23, 0xbfb8aa3b, v19
	v_exp_f32_e32 v20, v20
	v_exp_f32_e32 v21, v21
	v_exp_f32_e32 v22, v22
	v_exp_f32_e32 v23, v23
	s_nop 0
	v_add_f32_e32 v20, 1.0, v20
	v_add_f32_e32 v21, 1.0, v21
	v_add_f32_e32 v22, 1.0, v22
	v_add_f32_e32 v23, 1.0, v23
	v_div_scale_f32 v8, s[0:1], v20, v20, v16
	v_rcp_f32_e32 v9, v8
	s_nop 0
	v_fma_f32 v10, -v8, v9, 1.0
	v_fmac_f32_e32 v9, v10, v9
	v_div_scale_f32 v10, vcc, v16, v20, v16
	v_mul_f32_e32 v11, v10, v9
	v_fma_f32 v12, -v8, v11, v10
	v_fmac_f32_e32 v11, v12, v9
	v_fma_f32 v8, -v8, v11, v10
	v_div_fmas_f32 v8, v8, v9, v11
	v_div_fixup_f32 v24, v8, v20, v16
	v_div_scale_f32 v8, s[0:1], v21, v21, v17
	v_rcp_f32_e32 v9, v8
	s_nop 0
	v_fma_f32 v10, -v8, v9, 1.0
	v_fmac_f32_e32 v9, v10, v9
	v_div_scale_f32 v10, vcc, v17, v21, v17
	v_mul_f32_e32 v11, v10, v9
	v_fma_f32 v12, -v8, v11, v10
	v_fmac_f32_e32 v11, v12, v9
	v_fma_f32 v8, -v8, v11, v10
	v_div_fmas_f32 v8, v8, v9, v11
	v_div_fixup_f32 v25, v8, v21, v17
	v_div_scale_f32 v8, s[0:1], v22, v22, v18
	v_rcp_f32_e32 v9, v8
	s_nop 0
	v_fma_f32 v10, -v8, v9, 1.0
	v_fmac_f32_e32 v9, v10, v9
	v_div_scale_f32 v10, vcc, v18, v22, v18
	v_mul_f32_e32 v11, v10, v9
	v_fma_f32 v12, -v8, v11, v10
	v_fmac_f32_e32 v11, v12, v9
	v_fma_f32 v8, -v8, v11, v10
	v_div_fmas_f32 v8, v8, v9, v11
	v_div_fixup_f32 v26, v8, v22, v18
	v_div_scale_f32 v8, s[0:1], v23, v23, v19
	v_rcp_f32_e32 v9, v8
	s_nop 0
	v_fma_f32 v10, -v8, v9, 1.0
	v_fmac_f32_e32 v9, v10, v9
	v_div_scale_f32 v10, vcc, v19, v23, v19
	v_mul_f32_e32 v11, v10, v9
	v_fma_f32 v12, -v8, v11, v10
	v_fmac_f32_e32 v11, v12, v9
	v_fma_f32 v8, -v8, v11, v10
	v_div_fmas_f32 v8, v8, v9, v11
	v_div_fixup_f32 v27, v8, v23, v19
	v_mul_f32_e32 v24, v24, v44
	v_mul_f32_e32 v25, v25, v45
	v_mul_f32_e32 v26, v26, v46
	v_mul_f32_e32 v27, v27, v47
	v_mul_f32_e32 v24, v24, v6
	v_mul_f32_e32 v25, v25, v6
	v_mul_f32_e32 v26, v26, v6
	v_mul_f32_e32 v27, v27, v6
	v_cvt_pk_bf16_f32 v30, v24, v25
	v_cvt_pk_bf16_f32 v31, v26, v27
	global_store_dwordx2 v2, v[30:31], s[88:89] offset:48
	s_waitcnt vmcnt(7)
	v_lshlrev_b32_e32 v16, 16, v72
	v_and_b32_e32 v17, 0xffff0000, v72
	v_lshlrev_b32_e32 v18, 16, v73
	v_and_b32_e32 v19, 0xffff0000, v73
	v_mul_f32_e32 v20, 0xbfb8aa3b, v16
	v_mul_f32_e32 v21, 0xbfb8aa3b, v17
	v_mul_f32_e32 v22, 0xbfb8aa3b, v18
	v_mul_f32_e32 v23, 0xbfb8aa3b, v19
	v_exp_f32_e32 v20, v20
	v_exp_f32_e32 v21, v21
	v_exp_f32_e32 v22, v22
	v_exp_f32_e32 v23, v23
	s_nop 0
	v_add_f32_e32 v20, 1.0, v20
	v_add_f32_e32 v21, 1.0, v21
	v_add_f32_e32 v22, 1.0, v22
	v_add_f32_e32 v23, 1.0, v23
	v_div_scale_f32 v8, s[0:1], v20, v20, v16
	v_rcp_f32_e32 v9, v8
	s_nop 0
	v_fma_f32 v10, -v8, v9, 1.0
	v_fmac_f32_e32 v9, v10, v9
	v_div_scale_f32 v10, vcc, v16, v20, v16
	v_mul_f32_e32 v11, v10, v9
	v_fma_f32 v12, -v8, v11, v10
	v_fmac_f32_e32 v11, v12, v9
	v_fma_f32 v8, -v8, v11, v10
	v_div_fmas_f32 v8, v8, v9, v11
	v_div_fixup_f32 v24, v8, v20, v16
	v_div_scale_f32 v8, s[0:1], v21, v21, v17
	v_rcp_f32_e32 v9, v8
	s_nop 0
	v_fma_f32 v10, -v8, v9, 1.0
	v_fmac_f32_e32 v9, v10, v9
	v_div_scale_f32 v10, vcc, v17, v21, v17
	v_mul_f32_e32 v11, v10, v9
	v_fma_f32 v12, -v8, v11, v10
	v_fmac_f32_e32 v11, v12, v9
	v_fma_f32 v8, -v8, v11, v10
	v_div_fmas_f32 v8, v8, v9, v11
	v_div_fixup_f32 v25, v8, v21, v17
	v_div_scale_f32 v8, s[0:1], v22, v22, v18
	v_rcp_f32_e32 v9, v8
	s_nop 0
	v_fma_f32 v10, -v8, v9, 1.0
	v_fmac_f32_e32 v9, v10, v9
	v_div_scale_f32 v10, vcc, v18, v22, v18
	v_mul_f32_e32 v11, v10, v9
	v_fma_f32 v12, -v8, v11, v10
	v_fmac_f32_e32 v11, v12, v9
	v_fma_f32 v8, -v8, v11, v10
	v_div_fmas_f32 v8, v8, v9, v11
	v_div_fixup_f32 v26, v8, v22, v18
	v_div_scale_f32 v8, s[0:1], v23, v23, v19
	v_rcp_f32_e32 v9, v8
	s_nop 0
	v_fma_f32 v10, -v8, v9, 1.0
	v_fmac_f32_e32 v9, v10, v9
	v_div_scale_f32 v10, vcc, v19, v23, v19
	v_mul_f32_e32 v11, v10, v9
	v_fma_f32 v12, -v8, v11, v10
	v_fmac_f32_e32 v11, v12, v9
	v_fma_f32 v8, -v8, v11, v10
	v_div_fmas_f32 v8, v8, v9, v11
	v_div_fixup_f32 v27, v8, v23, v19
	v_mul_f32_e32 v24, v24, v48
	v_mul_f32_e32 v25, v25, v49
	v_mul_f32_e32 v26, v26, v50
	v_mul_f32_e32 v27, v27, v51
	v_mul_f32_e32 v24, v24, v6
	v_mul_f32_e32 v25, v25, v6
	v_mul_f32_e32 v26, v26, v6
	v_mul_f32_e32 v27, v27, v6
	v_cvt_pk_bf16_f32 v28, v24, v25
	v_cvt_pk_bf16_f32 v29, v26, v27
	global_store_dwordx2 v2, v[28:29], s[88:89] offset:64
	s_waitcnt vmcnt(7)
	v_lshlrev_b32_e32 v16, 16, v74
	v_and_b32_e32 v17, 0xffff0000, v74
	v_lshlrev_b32_e32 v18, 16, v75
	v_and_b32_e32 v19, 0xffff0000, v75
	v_mul_f32_e32 v20, 0xbfb8aa3b, v16
	v_mul_f32_e32 v21, 0xbfb8aa3b, v17
	v_mul_f32_e32 v22, 0xbfb8aa3b, v18
	v_mul_f32_e32 v23, 0xbfb8aa3b, v19
	v_exp_f32_e32 v20, v20
	v_exp_f32_e32 v21, v21
	v_exp_f32_e32 v22, v22
	v_exp_f32_e32 v23, v23
	s_nop 0
	v_add_f32_e32 v20, 1.0, v20
	v_add_f32_e32 v21, 1.0, v21
	v_add_f32_e32 v22, 1.0, v22
	v_add_f32_e32 v23, 1.0, v23
	v_div_scale_f32 v8, s[0:1], v20, v20, v16
	v_rcp_f32_e32 v9, v8
	s_nop 0
	v_fma_f32 v10, -v8, v9, 1.0
	v_fmac_f32_e32 v9, v10, v9
	v_div_scale_f32 v10, vcc, v16, v20, v16
	v_mul_f32_e32 v11, v10, v9
	v_fma_f32 v12, -v8, v11, v10
	v_fmac_f32_e32 v11, v12, v9
	v_fma_f32 v8, -v8, v11, v10
	v_div_fmas_f32 v8, v8, v9, v11
	v_div_fixup_f32 v24, v8, v20, v16
	v_div_scale_f32 v8, s[0:1], v21, v21, v17
	v_rcp_f32_e32 v9, v8
	s_nop 0
	v_fma_f32 v10, -v8, v9, 1.0
	v_fmac_f32_e32 v9, v10, v9
	v_div_scale_f32 v10, vcc, v17, v21, v17
	v_mul_f32_e32 v11, v10, v9
	v_fma_f32 v12, -v8, v11, v10
	v_fmac_f32_e32 v11, v12, v9
	v_fma_f32 v8, -v8, v11, v10
	v_div_fmas_f32 v8, v8, v9, v11
	v_div_fixup_f32 v25, v8, v21, v17
	v_div_scale_f32 v8, s[0:1], v22, v22, v18
	v_rcp_f32_e32 v9, v8
	s_nop 0
	v_fma_f32 v10, -v8, v9, 1.0
	v_fmac_f32_e32 v9, v10, v9
	v_div_scale_f32 v10, vcc, v18, v22, v18
	v_mul_f32_e32 v11, v10, v9
	v_fma_f32 v12, -v8, v11, v10
	v_fmac_f32_e32 v11, v12, v9
	v_fma_f32 v8, -v8, v11, v10
	v_div_fmas_f32 v8, v8, v9, v11
	v_div_fixup_f32 v26, v8, v22, v18
	v_div_scale_f32 v8, s[0:1], v23, v23, v19
	v_rcp_f32_e32 v9, v8
	s_nop 0
	v_fma_f32 v10, -v8, v9, 1.0
	v_fmac_f32_e32 v9, v10, v9
	v_div_scale_f32 v10, vcc, v19, v23, v19
	v_mul_f32_e32 v11, v10, v9
	v_fma_f32 v12, -v8, v11, v10
	v_fmac_f32_e32 v11, v12, v9
	v_fma_f32 v8, -v8, v11, v10
	v_div_fmas_f32 v8, v8, v9, v11
	v_div_fixup_f32 v27, v8, v23, v19
	v_mul_f32_e32 v24, v24, v52
	v_mul_f32_e32 v25, v25, v53
	v_mul_f32_e32 v26, v26, v54
	v_mul_f32_e32 v27, v27, v55
	v_mul_f32_e32 v24, v24, v6
	v_mul_f32_e32 v25, v25, v6
	v_mul_f32_e32 v26, v26, v6
	v_mul_f32_e32 v27, v27, v6
	v_cvt_pk_bf16_f32 v30, v24, v25
	v_cvt_pk_bf16_f32 v31, v26, v27
	global_store_dwordx2 v2, v[30:31], s[88:89] offset:80
	s_waitcnt vmcnt(7)
	v_lshlrev_b32_e32 v16, 16, v76
	v_and_b32_e32 v17, 0xffff0000, v76
	v_lshlrev_b32_e32 v18, 16, v77
	v_and_b32_e32 v19, 0xffff0000, v77
	v_mul_f32_e32 v20, 0xbfb8aa3b, v16
	v_mul_f32_e32 v21, 0xbfb8aa3b, v17
	v_mul_f32_e32 v22, 0xbfb8aa3b, v18
	v_mul_f32_e32 v23, 0xbfb8aa3b, v19
	v_exp_f32_e32 v20, v20
	v_exp_f32_e32 v21, v21
	v_exp_f32_e32 v22, v22
	v_exp_f32_e32 v23, v23
	s_nop 0
	v_add_f32_e32 v20, 1.0, v20
	v_add_f32_e32 v21, 1.0, v21
	v_add_f32_e32 v22, 1.0, v22
	v_add_f32_e32 v23, 1.0, v23
	v_div_scale_f32 v8, s[0:1], v20, v20, v16
	v_rcp_f32_e32 v9, v8
	s_nop 0
	v_fma_f32 v10, -v8, v9, 1.0
	v_fmac_f32_e32 v9, v10, v9
	v_div_scale_f32 v10, vcc, v16, v20, v16
	v_mul_f32_e32 v11, v10, v9
	v_fma_f32 v12, -v8, v11, v10
	v_fmac_f32_e32 v11, v12, v9
	v_fma_f32 v8, -v8, v11, v10
	v_div_fmas_f32 v8, v8, v9, v11
	v_div_fixup_f32 v24, v8, v20, v16
	v_div_scale_f32 v8, s[0:1], v21, v21, v17
	v_rcp_f32_e32 v9, v8
	s_nop 0
	v_fma_f32 v10, -v8, v9, 1.0
	v_fmac_f32_e32 v9, v10, v9
	v_div_scale_f32 v10, vcc, v17, v21, v17
	v_mul_f32_e32 v11, v10, v9
	v_fma_f32 v12, -v8, v11, v10
	v_fmac_f32_e32 v11, v12, v9
	v_fma_f32 v8, -v8, v11, v10
	v_div_fmas_f32 v8, v8, v9, v11
	v_div_fixup_f32 v25, v8, v21, v17
	v_div_scale_f32 v8, s[0:1], v22, v22, v18
	v_rcp_f32_e32 v9, v8
	s_nop 0
	v_fma_f32 v10, -v8, v9, 1.0
	v_fmac_f32_e32 v9, v10, v9
	v_div_scale_f32 v10, vcc, v18, v22, v18
	v_mul_f32_e32 v11, v10, v9
	v_fma_f32 v12, -v8, v11, v10
	v_fmac_f32_e32 v11, v12, v9
	v_fma_f32 v8, -v8, v11, v10
	v_div_fmas_f32 v8, v8, v9, v11
	v_div_fixup_f32 v26, v8, v22, v18
	v_div_scale_f32 v8, s[0:1], v23, v23, v19
	v_rcp_f32_e32 v9, v8
	s_nop 0
	v_fma_f32 v10, -v8, v9, 1.0
	v_fmac_f32_e32 v9, v10, v9
	v_div_scale_f32 v10, vcc, v19, v23, v19
	v_mul_f32_e32 v11, v10, v9
	v_fma_f32 v12, -v8, v11, v10
	v_fmac_f32_e32 v11, v12, v9
	v_fma_f32 v8, -v8, v11, v10
	v_div_fmas_f32 v8, v8, v9, v11
	v_div_fixup_f32 v27, v8, v23, v19
	v_mul_f32_e32 v24, v24, v56
	v_mul_f32_e32 v25, v25, v57
	v_mul_f32_e32 v26, v26, v58
	v_mul_f32_e32 v27, v27, v59
	v_mul_f32_e32 v24, v24, v6
	v_mul_f32_e32 v25, v25, v6
	v_mul_f32_e32 v26, v26, v6
	v_mul_f32_e32 v27, v27, v6
	v_cvt_pk_bf16_f32 v28, v24, v25
	v_cvt_pk_bf16_f32 v29, v26, v27
	global_store_dwordx2 v2, v[28:29], s[88:89] offset:96
	s_waitcnt vmcnt(7)
	v_lshlrev_b32_e32 v16, 16, v78
	v_and_b32_e32 v17, 0xffff0000, v78
	v_lshlrev_b32_e32 v18, 16, v79
	v_and_b32_e32 v19, 0xffff0000, v79
	v_mul_f32_e32 v20, 0xbfb8aa3b, v16
	v_mul_f32_e32 v21, 0xbfb8aa3b, v17
	v_mul_f32_e32 v22, 0xbfb8aa3b, v18
	v_mul_f32_e32 v23, 0xbfb8aa3b, v19
	v_exp_f32_e32 v20, v20
	v_exp_f32_e32 v21, v21
	v_exp_f32_e32 v22, v22
	v_exp_f32_e32 v23, v23
	s_nop 0
	v_add_f32_e32 v20, 1.0, v20
	v_add_f32_e32 v21, 1.0, v21
	v_add_f32_e32 v22, 1.0, v22
	v_add_f32_e32 v23, 1.0, v23
	v_div_scale_f32 v8, s[0:1], v20, v20, v16
	v_rcp_f32_e32 v9, v8
	s_nop 0
	v_fma_f32 v10, -v8, v9, 1.0
	v_fmac_f32_e32 v9, v10, v9
	v_div_scale_f32 v10, vcc, v16, v20, v16
	v_mul_f32_e32 v11, v10, v9
	v_fma_f32 v12, -v8, v11, v10
	v_fmac_f32_e32 v11, v12, v9
	v_fma_f32 v8, -v8, v11, v10
	v_div_fmas_f32 v8, v8, v9, v11
	v_div_fixup_f32 v24, v8, v20, v16
	v_div_scale_f32 v8, s[0:1], v21, v21, v17
	v_rcp_f32_e32 v9, v8
	s_nop 0
	v_fma_f32 v10, -v8, v9, 1.0
	v_fmac_f32_e32 v9, v10, v9
	v_div_scale_f32 v10, vcc, v17, v21, v17
	v_mul_f32_e32 v11, v10, v9
	v_fma_f32 v12, -v8, v11, v10
	v_fmac_f32_e32 v11, v12, v9
	v_fma_f32 v8, -v8, v11, v10
	v_div_fmas_f32 v8, v8, v9, v11
	v_div_fixup_f32 v25, v8, v21, v17
	v_div_scale_f32 v8, s[0:1], v22, v22, v18
	v_rcp_f32_e32 v9, v8
	s_nop 0
	v_fma_f32 v10, -v8, v9, 1.0
	v_fmac_f32_e32 v9, v10, v9
	v_div_scale_f32 v10, vcc, v18, v22, v18
	v_mul_f32_e32 v11, v10, v9
	v_fma_f32 v12, -v8, v11, v10
	v_fmac_f32_e32 v11, v12, v9
	v_fma_f32 v8, -v8, v11, v10
	v_div_fmas_f32 v8, v8, v9, v11
	v_div_fixup_f32 v26, v8, v22, v18
	v_div_scale_f32 v8, s[0:1], v23, v23, v19
	v_rcp_f32_e32 v9, v8
	s_nop 0
	v_fma_f32 v10, -v8, v9, 1.0
	v_fmac_f32_e32 v9, v10, v9
	v_div_scale_f32 v10, vcc, v19, v23, v19
	v_mul_f32_e32 v11, v10, v9
	v_fma_f32 v12, -v8, v11, v10
	v_fmac_f32_e32 v11, v12, v9
	v_fma_f32 v8, -v8, v11, v10
	v_div_fmas_f32 v8, v8, v9, v11
	v_div_fixup_f32 v27, v8, v23, v19
	v_mul_f32_e32 v24, v24, v60
	v_mul_f32_e32 v25, v25, v61
	v_mul_f32_e32 v26, v26, v62
	v_mul_f32_e32 v27, v27, v63
	v_mul_f32_e32 v24, v24, v6
	v_mul_f32_e32 v25, v25, v6
	v_mul_f32_e32 v26, v26, v6
	v_mul_f32_e32 v27, v27, v6
	v_cvt_pk_bf16_f32 v30, v24, v25
	v_cvt_pk_bf16_f32 v31, v26, v27
	global_store_dwordx2 v2, v[30:31], s[88:89] offset:112
	s_add_i32 s2, s2, s71
	v_readlane_b32 s0, v206, 49
	s_nop 0
	s_cmp_ge_u32 s2, s0
	s_cbranch_scc0 .LBB0_350
	s_branch .LBB0_343

.Lat_rare0:
	v_max_f32_e32 v167, v0, v0
	v_max_f32_e32 v168, v1, v1
	v_max_f32_e32 v167, v167, v168
	v_max3_f32 v167, v167, v2, v3
	v_max3_f32 v167, v167, v4, v5
	v_max3_f32 v167, v167, v6, v7
	v_max3_f32 v167, v167, v8, v9
	v_max3_f32 v167, v167, v10, v11
	v_max3_f32 v167, v167, v12, v13
	v_max3_f32 v167, v167, v14, v15
	v_mbcnt_lo_u32_b32 v168, -1, 0
	v_mbcnt_hi_u32_b32 v168, -1, v168
	v_xor_b32_e32 v168, 32, v168
	v_lshlrev_b32_e32 v168, 2, v168
	s_waitcnt lgkmcnt(0)
	ds_bpermute_b32 v169, v168, v167
	ds_bpermute_b32 v170, v168, v128
	s_mov_b32 s84, 1
	s_waitcnt lgkmcnt(1)
	v_max_f32_e32 v169, v169, v169
	v_max_f32_e32 v167, v167, v169
	s_waitcnt lgkmcnt(0)
	v_add_f32_e32 v170, v128, v170
	v_max_f32_e32 v169, 0, v167
	v_cmp_nle_f32_e32 vcc, s73, v170
	s_nop 1
	v_cndmask_b32_e32 v171, v169, v167, vcc
	v_exp_f32_e64 v172, -v171
	s_nop 0
	v_cndmask_b32_e64 v172, v172, 0, vcc
	v_add_f32_e32 v129, v129, v171
	v_mul_f32_e32 v128, v128, v172
	v_mul_f32_e32 v32, v32, v172
	v_mul_f32_e32 v33, v33, v172
	v_mul_f32_e32 v34, v34, v172
	v_mul_f32_e32 v35, v35, v172
	v_mul_f32_e32 v36, v36, v172
	v_mul_f32_e32 v37, v37, v172
	v_mul_f32_e32 v38, v38, v172
	v_mul_f32_e32 v39, v39, v172
	v_mul_f32_e32 v40, v40, v172
	v_mul_f32_e32 v41, v41, v172
	v_mul_f32_e32 v42, v42, v172
	v_mul_f32_e32 v43, v43, v172
	v_mul_f32_e32 v44, v44, v172
	v_mul_f32_e32 v45, v45, v172
	v_mul_f32_e32 v46, v46, v172
	v_mul_f32_e32 v47, v47, v172
	v_mul_f32_e32 v48, v48, v172
	v_mul_f32_e32 v49, v49, v172
	v_mul_f32_e32 v50, v50, v172
	v_mul_f32_e32 v51, v51, v172
	v_mul_f32_e32 v52, v52, v172
	v_mul_f32_e32 v53, v53, v172
	v_mul_f32_e32 v54, v54, v172
	v_mul_f32_e32 v55, v55, v172
	v_mul_f32_e32 v56, v56, v172
	v_mul_f32_e32 v57, v57, v172
	v_mul_f32_e32 v58, v58, v172
	v_mul_f32_e32 v59, v59, v172
	v_mul_f32_e32 v60, v60, v172
	v_mul_f32_e32 v61, v61, v172
	v_mul_f32_e32 v62, v62, v172
	v_mul_f32_e32 v63, v63, v172
	v_sub_f32_e32 v174, v0, v171
	v_exp_f32_e32 v64, v174
	v_sub_f32_e32 v174, v1, v171
	v_exp_f32_e32 v65, v174
	v_add_f32_e32 v136, 0, v64
	v_sub_f32_e32 v174, v2, v171
	v_exp_f32_e32 v66, v174
	v_add_f32_e32 v136, v65, v136
	v_sub_f32_e32 v174, v3, v171
	v_exp_f32_e32 v67, v174
	v_add_f32_e32 v136, v66, v136
	v_sub_f32_e32 v174, v4, v171
	v_exp_f32_e32 v68, v174
	v_add_f32_e32 v136, v67, v136
	v_sub_f32_e32 v174, v5, v171
	v_exp_f32_e32 v69, v174
	v_add_f32_e32 v136, v68, v136
	v_sub_f32_e32 v174, v6, v171
	v_exp_f32_e32 v70, v174
	v_add_f32_e32 v136, v69, v136
	v_sub_f32_e32 v174, v7, v171
	v_exp_f32_e32 v71, v174
	v_add_f32_e32 v136, v70, v136
	v_sub_f32_e32 v174, v8, v171
	v_exp_f32_e32 v72, v174
	v_add_f32_e32 v136, v71, v136
	v_sub_f32_e32 v174, v9, v171
	v_exp_f32_e32 v73, v174
	v_add_f32_e32 v136, v72, v136
	v_sub_f32_e32 v174, v10, v171
	v_exp_f32_e32 v74, v174
	v_add_f32_e32 v136, v73, v136
	v_sub_f32_e32 v174, v11, v171
	v_exp_f32_e32 v75, v174
	v_add_f32_e32 v136, v74, v136
	v_sub_f32_e32 v174, v12, v171
	v_exp_f32_e32 v76, v174
	v_add_f32_e32 v136, v75, v136
	v_sub_f32_e32 v174, v13, v171
	v_exp_f32_e32 v77, v174
	v_add_f32_e32 v136, v76, v136
	v_sub_f32_e32 v174, v14, v171
	v_exp_f32_e32 v78, v174
	v_add_f32_e32 v136, v77, v136
	v_sub_f32_e32 v174, v15, v171
	v_exp_f32_e32 v79, v174
	v_add_f32_e32 v136, v78, v136
	s_nop 0
	v_add_f32_e32 v134, v79, v136
	s_waitcnt lgkmcnt(0)
	s_branch .Lat_rare0_ret

.Lat_rare1:
	v_max_f32_e32 v167, v16, v16
	v_max_f32_e32 v168, v17, v17
	v_max_f32_e32 v167, v167, v168
	v_max3_f32 v167, v167, v18, v19
	v_max3_f32 v167, v167, v20, v21
	v_max3_f32 v167, v167, v22, v23
	v_max3_f32 v167, v167, v24, v25
	v_max3_f32 v167, v167, v26, v27
	v_max3_f32 v167, v167, v28, v29
	v_max3_f32 v167, v167, v30, v31
	v_mbcnt_lo_u32_b32 v168, -1, 0
	v_mbcnt_hi_u32_b32 v168, -1, v168
	v_xor_b32_e32 v168, 32, v168
	v_lshlrev_b32_e32 v168, 2, v168
	s_waitcnt lgkmcnt(0)
	ds_bpermute_b32 v169, v168, v167
	ds_bpermute_b32 v170, v168, v128
	s_mov_b32 s84, 1
	s_waitcnt lgkmcnt(1)
	v_max_f32_e32 v169, v169, v169
	v_max_f32_e32 v167, v167, v169
	s_waitcnt lgkmcnt(0)
	v_add_f32_e32 v170, v128, v170
	v_max_f32_e32 v169, 0, v167
	v_cmp_nle_f32_e32 vcc, s73, v170
	s_nop 1
	v_cndmask_b32_e32 v171, v169, v167, vcc
	v_exp_f32_e64 v172, -v171
	s_nop 0
	v_cndmask_b32_e64 v172, v172, 0, vcc
	v_add_f32_e32 v129, v129, v171
	v_mul_f32_e32 v128, v128, v172
	v_mul_f32_e32 v32, v32, v172
	v_mul_f32_e32 v33, v33, v172
	v_mul_f32_e32 v34, v34, v172
	v_mul_f32_e32 v35, v35, v172
	v_mul_f32_e32 v36, v36, v172
	v_mul_f32_e32 v37, v37, v172
	v_mul_f32_e32 v38, v38, v172
	v_mul_f32_e32 v39, v39, v172
	v_mul_f32_e32 v40, v40, v172
	v_mul_f32_e32 v41, v41, v172
	v_mul_f32_e32 v42, v42, v172
	v_mul_f32_e32 v43, v43, v172
	v_mul_f32_e32 v44, v44, v172
	v_mul_f32_e32 v45, v45, v172
	v_mul_f32_e32 v46, v46, v172
	v_mul_f32_e32 v47, v47, v172
	v_mul_f32_e32 v48, v48, v172
	v_mul_f32_e32 v49, v49, v172
	v_mul_f32_e32 v50, v50, v172
	v_mul_f32_e32 v51, v51, v172
	v_mul_f32_e32 v52, v52, v172
	v_mul_f32_e32 v53, v53, v172
	v_mul_f32_e32 v54, v54, v172
	v_mul_f32_e32 v55, v55, v172
	v_mul_f32_e32 v56, v56, v172
	v_mul_f32_e32 v57, v57, v172
	v_mul_f32_e32 v58, v58, v172
	v_mul_f32_e32 v59, v59, v172
	v_mul_f32_e32 v60, v60, v172
	v_mul_f32_e32 v61, v61, v172
	v_mul_f32_e32 v62, v62, v172
	v_mul_f32_e32 v63, v63, v172
	v_sub_f32_e32 v174, v16, v171
	v_exp_f32_e32 v80, v174
	v_sub_f32_e32 v174, v17, v171
	v_exp_f32_e32 v81, v174
	v_add_f32_e32 v136, 0, v80
	v_sub_f32_e32 v174, v18, v171
	v_exp_f32_e32 v82, v174
	v_add_f32_e32 v136, v81, v136
	v_sub_f32_e32 v174, v19, v171
	v_exp_f32_e32 v83, v174
	v_add_f32_e32 v136, v82, v136
	v_sub_f32_e32 v174, v20, v171
	v_exp_f32_e32 v84, v174
	v_add_f32_e32 v136, v83, v136
	v_sub_f32_e32 v174, v21, v171
	v_exp_f32_e32 v85, v174
	v_add_f32_e32 v136, v84, v136
	v_sub_f32_e32 v174, v22, v171
	v_exp_f32_e32 v86, v174
	v_add_f32_e32 v136, v85, v136
	v_sub_f32_e32 v174, v23, v171
	v_exp_f32_e32 v87, v174
	v_add_f32_e32 v136, v86, v136
	v_sub_f32_e32 v174, v24, v171
	v_exp_f32_e32 v88, v174
	v_add_f32_e32 v136, v87, v136
	v_sub_f32_e32 v174, v25, v171
	v_exp_f32_e32 v89, v174
	v_add_f32_e32 v136, v88, v136
	v_sub_f32_e32 v174, v26, v171
	v_exp_f32_e32 v90, v174
	v_add_f32_e32 v136, v89, v136
	v_sub_f32_e32 v174, v27, v171
	v_exp_f32_e32 v91, v174
	v_add_f32_e32 v136, v90, v136
	v_sub_f32_e32 v174, v28, v171
	v_exp_f32_e32 v92, v174
	v_add_f32_e32 v136, v91, v136
	v_sub_f32_e32 v174, v29, v171
	v_exp_f32_e32 v93, v174
	v_add_f32_e32 v136, v92, v136
	v_sub_f32_e32 v174, v30, v171
	v_exp_f32_e32 v94, v174
	v_add_f32_e32 v136, v93, v136
	v_sub_f32_e32 v174, v31, v171
	v_exp_f32_e32 v95, v174
	v_add_f32_e32 v136, v94, v136
	s_nop 0
	v_add_f32_e32 v134, v95, v136
	s_waitcnt lgkmcnt(0)
	s_branch .Lat_rare1_ret
